# P6 epilogue rewritten by hand: 6 of 16 output stores deferred into next tile K loop
# speedup vs baseline: 1.0004x; 1.0004x over previous
.LBB0_979:
	s_add_u32 s16, s14, 0x7a00000
	s_addc_u32 s17, s15, 0
	s_add_u32 s18, s14, 0x1fe40000
	s_addc_u32 s19, s15, 0
	s_lshl_b32 s24, s24, 5
	s_and_b32 s28, s24, 0x60
	s_mov_b64 s[24:25], 0x80
	s_add_i32 m0, s35, 0x18000
	v_lshl_add_u64 v[6:7], v[6:7], 0, s[24:25]
	s_lshl_b32 s11, s9, 13
	s_lshl_b32 s29, s28, 7
	s_waitcnt vmcnt(4)
	s_barrier
	global_load_lds_dwordx4 v[6:7], off
	v_lshl_add_u64 v[4:5], v[4:5], 0, s[24:25]
	s_add_i32 m0, s35, 0x1a000
	s_add_i32 s46, s35, 0x8000
	s_add_i32 s47, s35, 0xa000
	global_load_lds_dwordx4 v[4:5], off
	v_lshl_add_u64 v[2:3], v[2:3], 0, s[24:25]
	s_mov_b32 m0, s46
	s_add_u32 s26, s56, 0x40080
	global_load_lds_dwordx4 v[2:3], off
	v_lshl_add_u64 v[0:1], v[0:1], 0, s[24:25]
	s_mov_b32 m0, s47
	s_addc_u32 s27, s57, 0
	global_load_lds_dwordx4 v[0:1], off
	s_add_i32 m0, s35, 0x1c000
	v_lshl_add_u64 v[0:1], s[26:27], 0, v[130:131]
	global_load_lds_dwordx4 v[0:1], off
	v_lshl_add_u64 v[0:1], s[26:27], 0, v[134:135]
	s_add_i32 m0, s35, 0x1e000
	s_add_i32 s60, 0, 0x10000
	global_load_lds_dwordx4 v[0:1], off
	v_lshrrev_b32_e32 v1, 1, v8
	v_and_b32_e32 v1, 24, v1
	v_and_b32_e32 v0, 15, v8
	v_lshlrev_b32_e32 v2, 1, v1
	v_lshl_or_b32 v145, s9, 6, v0
	v_lshl_or_b32 v0, v0, 6, v2
	v_lshlrev_b32_e32 v2, 2, v8
	v_and_b32_e32 v2, 32, v2
	v_bitop3_b32 v3, v0, s11, v2 bitop3:0xde
	s_waitcnt vmcnt(0)
	v_bitop3_b32 v149, v0, s29, v2 bitop3:0xde
	v_lshlrev_b32_e32 v0, 14, v9
	v_and_b32_e32 v0, 0xffff8000, v0
	v_or_b32_e32 v151, s28, v1
	v_lshl_add_u32 v0, v10, 11, v0
	v_and_b32_e32 v1, 1, v9
	v_lshl_or_b32 v0, v1, 6, v0
	v_lshl_add_u32 v136, v11, 1, v0
	v_lshlrev_b32_e32 v0, 14, v12
	v_and_b32_e32 v0, 0xffff8000, v0
	s_waitcnt vmcnt(6)
	v_lshl_add_u32 v0, v13, 11, v0
	v_and_b32_e32 v1, 1, v12
	v_lshl_or_b32 v0, v1, 6, v0
	s_add_i32 s61, 0, 0x14000
	s_sext_i32_i8 s67, s8
	s_ashr_i32 s48, s22, 31
	s_mov_b32 s49, s22
	v_mov_b32_e32 v137, v131
	v_lshl_add_u32 v138, v14, 1, v0
	v_mov_b32_e32 v139, v131
	v_mov_b64_e32 v[140:141], 0x800
	v_mov_b64_e32 v[142:143], 0x7ff
	v_add_u32_e32 v155, s60, v149
	v_add_u32_e32 v159, 0, v3
	v_add_u32_e32 v162, s61, v149
	v_mov_b32_e32 v163, 0x358637bd
	s_mov_b32 s62, 0x800000
	s_mov_b64 s[26:27], 0x100000
	s_mov_b32 s63, 0x100000
	s_mov_b64 s[28:29], 0x120000
	s_mov_b32 s64, 0x120000
	s_mov_b64 s[30:31], 0x140000
	s_mov_b32 s65, 0x140000
	s_mov_b64 s[36:37], 0x160000
	s_mov_b32 s66, 0x160000
	s_barrier
	s_mov_b32 s32, 0
	v_mul_u32_u24_e32 v239, 0x2000, v145
	v_lshl_add_u32 v239, v151, 1, v239

.LBB0_987:
	ds_read_b128 v[164:167], v155
	ds_read_b128 v[168:171], v155 offset:1024
	ds_read_b128 v[172:175], v155 offset:2048
	ds_read_b128 v[176:179], v155 offset:3072
	s_add_u32 s56, s12, 0xfffc0080
	s_addc_u32 s57, s13, -1
	s_cmp_eq_u32 s71, 12
	s_cselect_b32 s59, s11, s57
	s_cselect_b32 s58, s51, s56
	s_cselect_b32 s57, s39, s70
	s_cselect_b32 s56, s68, s69
	v_lshl_add_u64 v[146:147], s[12:13], 0, v[136:137]
	s_add_i32 m0, s35, 0xc000
	ds_read_b128 v[180:183], v159
	ds_read_b128 v[184:187], v159 offset:1024
	ds_read_b128 v[188:191], v159 offset:2048
	ds_read_b128 v[192:195], v159 offset:3072
	ds_read_b128 v[196:199], v159 offset:4096
	ds_read_b128 v[200:203], v159 offset:5120
	ds_read_b128 v[206:209], v159 offset:6144
	ds_read_b128 v[210:213], v159 offset:7168
	global_load_lds_dwordx4 v[146:147], off
	v_lshl_add_u64 v[146:147], s[12:13], 0, v[138:139]
	s_add_i32 m0, s35, 0xe000
	s_nop 0
	global_load_lds_dwordx4 v[146:147], off
	s_waitcnt lgkmcnt(8)
	s_barrier
	s_waitcnt lgkmcnt(0)
	s_setprio 1
	s_waitcnt lgkmcnt(0)
	v_mfma_f32_16x16x32_bf16 v[124:127], v[164:167], v[180:183], v[124:127]
	v_mfma_f32_16x16x32_bf16 v[120:123], v[172:175], v[180:183], v[120:123]
	v_mfma_f32_16x16x32_bf16 v[108:111], v[164:167], v[188:191], v[108:111]
	v_mfma_f32_16x16x32_bf16 v[104:107], v[172:175], v[188:191], v[104:107]
	v_mfma_f32_16x16x32_bf16 v[92:95], v[164:167], v[196:199], v[92:95]
	v_mfma_f32_16x16x32_bf16 v[88:91], v[172:175], v[196:199], v[88:91]
	v_mfma_f32_16x16x32_bf16 v[76:79], v[164:167], v[206:209], v[76:79]
	v_mfma_f32_16x16x32_bf16 v[72:75], v[172:175], v[206:209], v[72:75]
	v_mfma_f32_16x16x32_bf16 v[124:127], v[168:171], v[184:187], v[124:127]
	v_mfma_f32_16x16x32_bf16 v[120:123], v[176:179], v[184:187], v[120:123]
	v_mfma_f32_16x16x32_bf16 v[108:111], v[168:171], v[192:195], v[108:111]
	v_mfma_f32_16x16x32_bf16 v[104:107], v[176:179], v[192:195], v[104:107]
	v_mfma_f32_16x16x32_bf16 v[92:95], v[168:171], v[200:203], v[92:95]
	v_mfma_f32_16x16x32_bf16 v[88:91], v[176:179], v[200:203], v[88:91]
	v_mfma_f32_16x16x32_bf16 v[76:79], v[168:171], v[210:213], v[76:79]
	v_mfma_f32_16x16x32_bf16 v[72:75], v[176:179], v[210:213], v[72:75]
	s_setprio 0
	s_barrier
	s_add_i32 s72, s60, s34
	v_lshl_add_u64 v[146:147], s[56:57], 0, v[130:131]
	s_mov_b32 m0, s72
	ds_read_b128 v[214:217], v162
	ds_read_b128 v[218:221], v162 offset:1024
	ds_read_b128 v[222:225], v162 offset:2048
	ds_read_b128 v[226:229], v162 offset:3072
	global_load_lds_dwordx4 v[146:147], off
	v_lshl_add_u64 v[152:153], s[56:57], 0, v[134:135]
	s_add_i32 m0, s72, 0x2000
	s_nop 0
	global_load_lds_dwordx4 v[152:153], off
	s_barrier
	s_waitcnt lgkmcnt(0)
	s_setprio 1
	s_waitcnt lgkmcnt(0)
	v_mfma_f32_16x16x32_bf16 v[116:119], v[214:217], v[180:183], v[116:119]
	v_mfma_f32_16x16x32_bf16 v[112:115], v[222:225], v[180:183], v[112:115]
	v_mfma_f32_16x16x32_bf16 v[100:103], v[214:217], v[188:191], v[100:103]
	v_mfma_f32_16x16x32_bf16 v[96:99], v[222:225], v[188:191], v[96:99]
	v_mfma_f32_16x16x32_bf16 v[84:87], v[214:217], v[196:199], v[84:87]
	v_mfma_f32_16x16x32_bf16 v[80:83], v[222:225], v[196:199], v[80:83]
	v_mfma_f32_16x16x32_bf16 v[68:71], v[214:217], v[206:209], v[68:71]
	v_mfma_f32_16x16x32_bf16 v[64:67], v[222:225], v[206:209], v[64:67]
	v_mfma_f32_16x16x32_bf16 v[116:119], v[218:221], v[184:187], v[116:119]
	v_mfma_f32_16x16x32_bf16 v[112:115], v[226:229], v[184:187], v[112:115]
	v_mfma_f32_16x16x32_bf16 v[100:103], v[218:221], v[192:195], v[100:103]
	v_mfma_f32_16x16x32_bf16 v[96:99], v[226:229], v[192:195], v[96:99]
	v_mfma_f32_16x16x32_bf16 v[84:87], v[218:221], v[200:203], v[84:87]
	v_mfma_f32_16x16x32_bf16 v[80:83], v[226:229], v[200:203], v[80:83]
	v_mfma_f32_16x16x32_bf16 v[68:71], v[218:221], v[210:213], v[68:71]
	v_mfma_f32_16x16x32_bf16 v[64:67], v[226:229], v[210:213], v[64:67]
	s_setprio 0
	s_mov_b32 m0, s35
	v_lshl_add_u64 v[156:157], s[58:59], 0, v[128:129]
	s_barrier
	ds_read_b128 v[180:183], v159 offset:16384
	ds_read_b128 v[184:187], v159 offset:17408
	ds_read_b128 v[188:191], v159 offset:18432
	ds_read_b128 v[192:195], v159 offset:19456
	ds_read_b128 v[196:199], v159 offset:20480
	ds_read_b128 v[200:203], v159 offset:21504
	ds_read_b128 v[206:209], v159 offset:22528
	ds_read_b128 v[210:213], v159 offset:23552
	global_load_lds_dwordx4 v[156:157], off
	v_lshl_add_u64 v[160:161], s[58:59], 0, v[132:133]
	s_mov_b32 m0, s42
	s_nop 0
	global_load_lds_dwordx4 v[160:161], off
	s_barrier
	s_waitcnt lgkmcnt(0)
	s_setprio 1
	s_waitcnt lgkmcnt(0)
	v_mfma_f32_16x16x32_bf16 v[60:63], v[164:167], v[180:183], v[60:63]
	v_mfma_f32_16x16x32_bf16 v[56:59], v[172:175], v[180:183], v[56:59]
	v_mfma_f32_16x16x32_bf16 v[44:47], v[164:167], v[188:191], v[44:47]
	v_mfma_f32_16x16x32_bf16 v[40:43], v[172:175], v[188:191], v[40:43]
	v_mfma_f32_16x16x32_bf16 v[28:31], v[164:167], v[196:199], v[28:31]
	v_mfma_f32_16x16x32_bf16 v[24:27], v[172:175], v[196:199], v[24:27]
	v_mfma_f32_16x16x32_bf16 v[12:15], v[164:167], v[206:209], v[12:15]
	v_mfma_f32_16x16x32_bf16 v[8:11], v[172:175], v[206:209], v[8:11]
	v_mfma_f32_16x16x32_bf16 v[60:63], v[168:171], v[184:187], v[60:63]
	v_mfma_f32_16x16x32_bf16 v[56:59], v[176:179], v[184:187], v[56:59]
	v_mfma_f32_16x16x32_bf16 v[44:47], v[168:171], v[192:195], v[44:47]
	v_mfma_f32_16x16x32_bf16 v[40:43], v[176:179], v[192:195], v[40:43]
	v_mfma_f32_16x16x32_bf16 v[28:31], v[168:171], v[200:203], v[28:31]
	v_mfma_f32_16x16x32_bf16 v[24:27], v[176:179], v[200:203], v[24:27]
	v_mfma_f32_16x16x32_bf16 v[12:15], v[168:171], v[210:213], v[12:15]
	v_mfma_f32_16x16x32_bf16 v[8:11], v[176:179], v[210:213], v[8:11]
	s_setprio 0
	s_barrier
	s_add_u32 s72, s56, 0x40000
	s_addc_u32 s73, s57, 0
	s_add_i32 s74, s61, s34
	v_lshl_add_u64 v[164:165], s[72:73], 0, v[130:131]
	s_mov_b32 m0, s74
	s_nop 0
	global_load_lds_dwordx4 v[164:165], off
	v_lshl_add_u64 v[164:165], s[72:73], 0, v[134:135]
	s_add_i32 m0, s74, 0x2000
	s_nop 0
	global_load_lds_dwordx4 v[164:165], off
	s_waitcnt vmcnt(6)
	s_cmp_gt_u32 s71, 4
	s_cbranch_scc1 .Lds_P6_a_done
	s_cmp_eq_u32 s32, 0
	s_cbranch_scc1 .Lds_P6_a_done
	s_cmp_eq_u32 s71, 0
	s_cbranch_scc1 .Lds_P6_a_0
	s_cmp_eq_u32 s71, 2
	s_cbranch_scc1 .Lds_P6_a_1
	s_add_u32 s100, s98, 0x160000
	s_addc_u32 s101, s99, 0
	global_store_dwordx4 v239, v[248:251], s[100:101]
	s_branch .Lds_P6_a_done
.Lds_P6_a_1:
	s_add_u32 s100, s98, 0x140000
	s_addc_u32 s101, s99, 0
	global_store_dwordx4 v239, v[240:243], s[100:101]
	s_branch .Lds_P6_a_done
.Lds_P6_a_0:
	s_add_u32 s100, s98, 0x120000
	s_addc_u32 s101, s99, 0
	global_store_dwordx4 v239, v[230:233], s[100:101]
.Lds_P6_a_done:
	s_barrier
	s_setprio 1
	v_mfma_f32_16x16x32_bf16 v[52:55], v[214:217], v[180:183], v[52:55]
	v_mfma_f32_16x16x32_bf16 v[48:51], v[222:225], v[180:183], v[48:51]
	v_mfma_f32_16x16x32_bf16 v[36:39], v[214:217], v[188:191], v[36:39]
	v_mfma_f32_16x16x32_bf16 v[32:35], v[222:225], v[188:191], v[32:35]
	v_mfma_f32_16x16x32_bf16 v[20:23], v[214:217], v[196:199], v[20:23]
	v_mfma_f32_16x16x32_bf16 v[16:19], v[222:225], v[196:199], v[16:19]
	v_mfma_f32_16x16x32_bf16 v[4:7], v[214:217], v[206:209], v[4:7]
	v_mfma_f32_16x16x32_bf16 v[0:3], v[222:225], v[206:209], v[0:3]
	v_mfma_f32_16x16x32_bf16 v[52:55], v[218:221], v[184:187], v[52:55]
	v_mfma_f32_16x16x32_bf16 v[48:51], v[226:229], v[184:187], v[48:51]
	v_mfma_f32_16x16x32_bf16 v[36:39], v[218:221], v[192:195], v[36:39]
	v_mfma_f32_16x16x32_bf16 v[32:35], v[226:229], v[192:195], v[32:35]
	v_mfma_f32_16x16x32_bf16 v[20:23], v[218:221], v[200:203], v[20:23]
	v_mfma_f32_16x16x32_bf16 v[16:19], v[226:229], v[200:203], v[16:19]
	v_mfma_f32_16x16x32_bf16 v[4:7], v[218:221], v[210:213], v[4:7]
	v_mfma_f32_16x16x32_bf16 v[0:3], v[226:229], v[210:213], v[0:3]
	s_setprio 0
	s_add_i32 s72, 0, 0x18000
	v_add_u32_e32 v144, s72, v149
	s_barrier
	ds_read_b128 v[164:167], v144
	ds_read_b128 v[168:171], v144 offset:1024
	ds_read_b128 v[172:175], v144 offset:2048
	ds_read_b128 v[176:179], v144 offset:3072
	s_add_u32 s58, s58, 0x40000
	s_addc_u32 s59, s59, 0
	s_mov_b32 m0, s43
	v_lshl_add_u64 v[214:215], s[58:59], 0, v[128:129]
	ds_read_b128 v[180:183], v159 offset:32768
	ds_read_b128 v[184:187], v159 offset:33792
	ds_read_b128 v[188:191], v159 offset:34816
	ds_read_b128 v[192:195], v159 offset:35840
	ds_read_b128 v[196:199], v159 offset:36864
	ds_read_b128 v[200:203], v159 offset:37888
	ds_read_b128 v[206:209], v159 offset:38912
	ds_read_b128 v[210:213], v159 offset:39936
	global_load_lds_dwordx4 v[214:215], off
	v_lshl_add_u64 v[214:215], s[58:59], 0, v[132:133]
	s_mov_b32 m0, s44
	s_nop 0
	global_load_lds_dwordx4 v[214:215], off
	s_waitcnt lgkmcnt(8)
	s_barrier
	s_waitcnt lgkmcnt(0)
	s_setprio 1
	s_waitcnt lgkmcnt(0)
	v_mfma_f32_16x16x32_bf16 v[124:127], v[164:167], v[180:183], v[124:127]
	v_mfma_f32_16x16x32_bf16 v[120:123], v[172:175], v[180:183], v[120:123]
	v_mfma_f32_16x16x32_bf16 v[108:111], v[164:167], v[188:191], v[108:111]
	v_mfma_f32_16x16x32_bf16 v[104:107], v[172:175], v[188:191], v[104:107]
	v_mfma_f32_16x16x32_bf16 v[92:95], v[164:167], v[196:199], v[92:95]
	v_mfma_f32_16x16x32_bf16 v[88:91], v[172:175], v[196:199], v[88:91]
	v_mfma_f32_16x16x32_bf16 v[76:79], v[164:167], v[206:209], v[76:79]
	v_mfma_f32_16x16x32_bf16 v[72:75], v[172:175], v[206:209], v[72:75]
	v_mfma_f32_16x16x32_bf16 v[124:127], v[168:171], v[184:187], v[124:127]
	v_mfma_f32_16x16x32_bf16 v[120:123], v[176:179], v[184:187], v[120:123]
	v_mfma_f32_16x16x32_bf16 v[108:111], v[168:171], v[192:195], v[108:111]
	v_mfma_f32_16x16x32_bf16 v[104:107], v[176:179], v[192:195], v[104:107]
	v_mfma_f32_16x16x32_bf16 v[92:95], v[168:171], v[200:203], v[92:95]
	v_mfma_f32_16x16x32_bf16 v[88:91], v[176:179], v[200:203], v[88:91]
	v_mfma_f32_16x16x32_bf16 v[76:79], v[168:171], v[210:213], v[76:79]
	v_mfma_f32_16x16x32_bf16 v[72:75], v[176:179], v[210:213], v[72:75]
	s_setprio 0
	s_barrier
	s_add_i32 s58, 0, 0x1c000
	s_add_i32 s59, s72, s34
	v_add_u32_e32 v144, s58, v149
	v_lshl_add_u64 v[146:147], v[146:147], 0, s[24:25]
	s_mov_b32 m0, s59
	ds_read_b128 v[214:217], v144
	ds_read_b128 v[218:221], v144 offset:1024
	ds_read_b128 v[222:225], v144 offset:2048
	ds_read_b128 v[226:229], v144 offset:3072
	global_load_lds_dwordx4 v[146:147], off
	v_lshl_add_u64 v[146:147], v[152:153], 0, s[24:25]
	s_add_i32 m0, s59, 0x2000
	s_nop 0
	global_load_lds_dwordx4 v[146:147], off
	s_barrier
	s_waitcnt lgkmcnt(0)
	s_setprio 1
	s_waitcnt lgkmcnt(0)
	v_mfma_f32_16x16x32_bf16 v[116:119], v[214:217], v[180:183], v[116:119]
	v_mfma_f32_16x16x32_bf16 v[112:115], v[222:225], v[180:183], v[112:115]
	v_mfma_f32_16x16x32_bf16 v[100:103], v[214:217], v[188:191], v[100:103]
	v_mfma_f32_16x16x32_bf16 v[96:99], v[222:225], v[188:191], v[96:99]
	v_mfma_f32_16x16x32_bf16 v[84:87], v[214:217], v[196:199], v[84:87]
	v_mfma_f32_16x16x32_bf16 v[80:83], v[222:225], v[196:199], v[80:83]
	v_mfma_f32_16x16x32_bf16 v[68:71], v[214:217], v[206:209], v[68:71]
	v_mfma_f32_16x16x32_bf16 v[64:67], v[222:225], v[206:209], v[64:67]
	v_mfma_f32_16x16x32_bf16 v[116:119], v[218:221], v[184:187], v[116:119]
	v_mfma_f32_16x16x32_bf16 v[112:115], v[226:229], v[184:187], v[112:115]
	v_mfma_f32_16x16x32_bf16 v[100:103], v[218:221], v[192:195], v[100:103]
	v_mfma_f32_16x16x32_bf16 v[96:99], v[226:229], v[192:195], v[96:99]
	v_mfma_f32_16x16x32_bf16 v[84:87], v[218:221], v[200:203], v[84:87]
	v_mfma_f32_16x16x32_bf16 v[80:83], v[226:229], v[200:203], v[80:83]
	v_mfma_f32_16x16x32_bf16 v[68:71], v[218:221], v[210:213], v[68:71]
	v_mfma_f32_16x16x32_bf16 v[64:67], v[226:229], v[210:213], v[64:67]
	s_setprio 0
	s_mov_b32 m0, s46
	v_lshl_add_u64 v[146:147], v[156:157], 0, s[24:25]
	s_barrier
	ds_read_b128 v[180:183], v159 offset:49152
	ds_read_b128 v[184:187], v159 offset:50176
	ds_read_b128 v[188:191], v159 offset:51200
	ds_read_b128 v[192:195], v159 offset:52224
	ds_read_b128 v[196:199], v159 offset:53248
	ds_read_b128 v[200:203], v159 offset:54272
	ds_read_b128 v[206:209], v159 offset:55296
	ds_read_b128 v[210:213], v159 offset:56320
	global_load_lds_dwordx4 v[146:147], off
	v_lshl_add_u64 v[146:147], v[160:161], 0, s[24:25]
	s_mov_b32 m0, s47
	s_nop 0
	global_load_lds_dwordx4 v[146:147], off
	s_barrier
	s_waitcnt lgkmcnt(0)
	s_setprio 1
	s_waitcnt lgkmcnt(0)
	v_mfma_f32_16x16x32_bf16 v[60:63], v[164:167], v[180:183], v[60:63]
	v_mfma_f32_16x16x32_bf16 v[56:59], v[172:175], v[180:183], v[56:59]
	v_mfma_f32_16x16x32_bf16 v[44:47], v[164:167], v[188:191], v[44:47]
	v_mfma_f32_16x16x32_bf16 v[40:43], v[172:175], v[188:191], v[40:43]
	v_mfma_f32_16x16x32_bf16 v[28:31], v[164:167], v[196:199], v[28:31]
	v_mfma_f32_16x16x32_bf16 v[24:27], v[172:175], v[196:199], v[24:27]
	v_mfma_f32_16x16x32_bf16 v[12:15], v[164:167], v[206:209], v[12:15]
	v_mfma_f32_16x16x32_bf16 v[8:11], v[172:175], v[206:209], v[8:11]
	v_mfma_f32_16x16x32_bf16 v[60:63], v[168:171], v[184:187], v[60:63]
	v_mfma_f32_16x16x32_bf16 v[56:59], v[176:179], v[184:187], v[56:59]
	v_mfma_f32_16x16x32_bf16 v[44:47], v[168:171], v[192:195], v[44:47]
	v_mfma_f32_16x16x32_bf16 v[40:43], v[176:179], v[192:195], v[40:43]
	v_mfma_f32_16x16x32_bf16 v[28:31], v[168:171], v[200:203], v[28:31]
	v_mfma_f32_16x16x32_bf16 v[24:27], v[176:179], v[200:203], v[24:27]
	v_mfma_f32_16x16x32_bf16 v[12:15], v[168:171], v[210:213], v[12:15]
	v_mfma_f32_16x16x32_bf16 v[8:11], v[176:179], v[210:213], v[8:11]
	s_setprio 0
	s_barrier
	s_add_u32 s56, s56, 0x40080
	s_addc_u32 s57, s57, 0
	s_add_i32 s58, s58, s34
	v_lshl_add_u64 v[146:147], s[56:57], 0, v[130:131]
	s_mov_b32 m0, s58
	s_nop 0
	global_load_lds_dwordx4 v[146:147], off
	v_lshl_add_u64 v[146:147], s[56:57], 0, v[134:135]
	s_add_i32 m0, s58, 0x2000
	s_nop 0
	global_load_lds_dwordx4 v[146:147], off
	s_waitcnt vmcnt(6)
	s_cmp_gt_u32 s71, 4
	s_cbranch_scc1 .Lds_P6_b_done
	s_cmp_eq_u32 s32, 0
	s_cbranch_scc1 .Lds_P6_b_done
	s_cmp_eq_u32 s71, 0
	s_cbranch_scc1 .Lds_P6_b_0
	s_cmp_eq_u32 s71, 2
	s_cbranch_scc1 .Lds_P6_b_1
	s_add_u32 s100, s98, 0x160000
	s_addc_u32 s101, s99, 0
	global_store_dwordx4 v239, v[252:255], s[100:101] offset:256
	s_branch .Lds_P6_b_done
.Lds_P6_b_1:
	s_add_u32 s100, s98, 0x140000
	s_addc_u32 s101, s99, 0
	global_store_dwordx4 v239, v[244:247], s[100:101] offset:256
	s_branch .Lds_P6_b_done
.Lds_P6_b_0:
	s_add_u32 s100, s98, 0x120000
	s_addc_u32 s101, s99, 0
	global_store_dwordx4 v239, v[234:237], s[100:101] offset:256
.Lds_P6_b_done:
	s_barrier
	s_setprio 1
	v_mfma_f32_16x16x32_bf16 v[52:55], v[214:217], v[180:183], v[52:55]
	v_mfma_f32_16x16x32_bf16 v[48:51], v[222:225], v[180:183], v[48:51]
	v_mfma_f32_16x16x32_bf16 v[36:39], v[214:217], v[188:191], v[36:39]
	v_mfma_f32_16x16x32_bf16 v[32:35], v[222:225], v[188:191], v[32:35]
	v_mfma_f32_16x16x32_bf16 v[20:23], v[214:217], v[196:199], v[20:23]
	v_mfma_f32_16x16x32_bf16 v[16:19], v[222:225], v[196:199], v[16:19]
	v_mfma_f32_16x16x32_bf16 v[4:7], v[214:217], v[206:209], v[4:7]
	v_mfma_f32_16x16x32_bf16 v[0:3], v[222:225], v[206:209], v[0:3]
	v_mfma_f32_16x16x32_bf16 v[52:55], v[218:221], v[184:187], v[52:55]
	v_mfma_f32_16x16x32_bf16 v[48:51], v[226:229], v[184:187], v[48:51]
	v_mfma_f32_16x16x32_bf16 v[36:39], v[218:221], v[192:195], v[36:39]
	v_mfma_f32_16x16x32_bf16 v[32:35], v[226:229], v[192:195], v[32:35]
	v_mfma_f32_16x16x32_bf16 v[20:23], v[218:221], v[200:203], v[20:23]
	v_mfma_f32_16x16x32_bf16 v[16:19], v[226:229], v[200:203], v[16:19]
	v_mfma_f32_16x16x32_bf16 v[4:7], v[218:221], v[210:213], v[4:7]
	v_mfma_f32_16x16x32_bf16 v[0:3], v[226:229], v[210:213], v[0:3]
	s_setprio 0
	s_add_i32 s71, s71, 2
	s_add_u32 s12, s12, 0x100
	s_addc_u32 s13, s13, 0
	s_add_u32 s69, s69, 0x100
	s_addc_u32 s70, s70, 0
	s_cmp_gt_u32 s71, 13
	s_barrier
	s_cbranch_scc0 .LBB0_987
.Lepi_P6_start:
	s_lshl_b32 s82, s10, 11
	s_add_u32 s100, s18, s82
	s_addc_u32 s101, s19, 0
	v_lshlrev_b32_e32 v164, 3, v145
	global_load_dwordx2 v[166:167], v164, s[100:101]
	global_load_dwordx2 v[168:169], v164, s[100:101] offset:128
	global_load_dwordx2 v[170:171], v164, s[100:101] offset:256
	global_load_dwordx2 v[172:173], v164, s[100:101] offset:384
	global_load_dwordx2 v[174:175], v164, s[100:101] offset:1024
	global_load_dwordx2 v[176:177], v164, s[100:101] offset:1152
	global_load_dwordx2 v[178:179], v164, s[100:101] offset:1280
	global_load_dwordx2 v[180:181], v164, s[100:101] offset:1408
	s_mul_i32 s82, s10, 0x200000
	s_lshl_b32 s84, s67, 9
	s_add_u32 s82, s82, s84
	s_add_u32 s84, s16, s82
	s_addc_u32 s85, s17, 0
	v_mov_b32_e32 v165, 0x358637bd
	s_waitcnt vmcnt(0)
	v_ffbh_u32_e32 v190, v167
	v_ffbh_u32_e32 v191, v169
	v_ffbh_u32_e32 v192, v171
	v_ffbh_u32_e32 v193, v173
	v_ffbh_u32_e32 v194, v175
	v_ffbh_u32_e32 v195, v177
	v_ffbh_u32_e32 v196, v179
	v_ffbh_u32_e32 v197, v181
	v_min_u32_e32 v190, 32, v190
	v_min_u32_e32 v191, 32, v191
	v_min_u32_e32 v192, 32, v192
	v_min_u32_e32 v193, 32, v193
	v_min_u32_e32 v194, 32, v194
	v_min_u32_e32 v195, 32, v195
	v_min_u32_e32 v196, 32, v196
	v_min_u32_e32 v197, 32, v197
	v_lshlrev_b64 v[166:167], v190, v[166:167]
	v_lshlrev_b64 v[168:169], v191, v[168:169]
	v_lshlrev_b64 v[170:171], v192, v[170:171]
	v_lshlrev_b64 v[172:173], v193, v[172:173]
	v_lshlrev_b64 v[174:175], v194, v[174:175]
	v_lshlrev_b64 v[176:177], v195, v[176:177]
	v_lshlrev_b64 v[178:179], v196, v[178:179]
	v_lshlrev_b64 v[180:181], v197, v[180:181]
	v_min_u32_e32 v166, 1, v166
	v_min_u32_e32 v168, 1, v168
	v_min_u32_e32 v170, 1, v170
	v_min_u32_e32 v172, 1, v172
	v_min_u32_e32 v174, 1, v174
	v_min_u32_e32 v176, 1, v176
	v_min_u32_e32 v178, 1, v178
	v_min_u32_e32 v180, 1, v180
	v_or_b32_e32 v167, v167, v166
	v_or_b32_e32 v169, v169, v168
	v_or_b32_e32 v171, v171, v170
	v_or_b32_e32 v173, v173, v172
	v_or_b32_e32 v175, v175, v174
	v_or_b32_e32 v177, v177, v176
	v_or_b32_e32 v179, v179, v178
	v_or_b32_e32 v181, v181, v180
	v_cvt_f32_u32_e32 v167, v167
	v_cvt_f32_u32_e32 v169, v169
	v_cvt_f32_u32_e32 v171, v171
	v_cvt_f32_u32_e32 v173, v173
	v_cvt_f32_u32_e32 v175, v175
	v_cvt_f32_u32_e32 v177, v177
	v_cvt_f32_u32_e32 v179, v179
	v_cvt_f32_u32_e32 v181, v181
	v_sub_u32_e32 v190, 32, v190
	v_sub_u32_e32 v191, 32, v191
	v_sub_u32_e32 v192, 32, v192
	v_sub_u32_e32 v193, 32, v193
	v_sub_u32_e32 v194, 32, v194
	v_sub_u32_e32 v195, 32, v195
	v_sub_u32_e32 v196, 32, v196
	v_sub_u32_e32 v197, 32, v197
	v_ldexp_f32 v167, v167, v190
	v_ldexp_f32 v169, v169, v191
	v_ldexp_f32 v171, v171, v192
	v_ldexp_f32 v173, v173, v193
	v_ldexp_f32 v175, v175, v194
	v_ldexp_f32 v177, v177, v195
	v_ldexp_f32 v179, v179, v196
	v_ldexp_f32 v181, v181, v197
	v_fmamk_f32 v167, v167, 0x2e800000, v165
	v_fmamk_f32 v169, v169, 0x2e800000, v165
	v_fmamk_f32 v171, v171, 0x2e800000, v165
	v_fmamk_f32 v173, v173, 0x2e800000, v165
	v_fmamk_f32 v175, v175, 0x2e800000, v165
	v_fmamk_f32 v177, v177, 0x2e800000, v165
	v_fmamk_f32 v179, v179, 0x2e800000, v165
	v_fmamk_f32 v181, v181, 0x2e800000, v165
	v_rsq_f32_e32 v182, v167
	v_rsq_f32_e32 v183, v169
	v_rsq_f32_e32 v184, v171
	v_rsq_f32_e32 v185, v173
	v_rsq_f32_e32 v186, v175
	v_rsq_f32_e32 v187, v177
	v_rsq_f32_e32 v188, v179
	v_rsq_f32_e32 v189, v181
	s_nop 0
	v_pk_mul_f32 v[120:121], v[120:121], v[182:183] op_sel_hi:[1,0]
	v_pk_mul_f32 v[122:123], v[122:123], v[182:183] op_sel_hi:[1,0]
	v_pk_mul_f32 v[124:125], v[124:125], v[182:183] op_sel_hi:[1,0]
	v_pk_mul_f32 v[126:127], v[126:127], v[182:183] op_sel_hi:[1,0]
	v_max_f32_e32 v120, 0, v120
	v_max_f32_e32 v121, 0, v121
	v_max_f32_e32 v122, 0, v122
	v_max_f32_e32 v123, 0, v123
	v_max_f32_e32 v124, 0, v124
	v_max_f32_e32 v125, 0, v125
	v_max_f32_e32 v126, 0, v126
	v_max_f32_e32 v127, 0, v127
	v_pk_mul_f32 v[120:121], v[120:121], v[120:121]
	v_pk_mul_f32 v[122:123], v[122:123], v[122:123]
	v_pk_mul_f32 v[124:125], v[124:125], v[124:125]
	v_pk_mul_f32 v[126:127], v[126:127], v[126:127]
	v_cvt_pk_bf16_f32 v124, v124, v125
	v_cvt_pk_bf16_f32 v125, v126, v127
	v_cvt_pk_bf16_f32 v126, v120, v121
	v_cvt_pk_bf16_f32 v127, v122, v123
	global_store_dwordx4 v239, v[124:127], s[84:85]
	v_pk_mul_f32 v[112:113], v[112:113], v[182:183] op_sel_hi:[1,0]
	v_pk_mul_f32 v[114:115], v[114:115], v[182:183] op_sel_hi:[1,0]
	v_pk_mul_f32 v[116:117], v[116:117], v[182:183] op_sel_hi:[1,0]
	v_pk_mul_f32 v[118:119], v[118:119], v[182:183] op_sel_hi:[1,0]
	v_max_f32_e32 v112, 0, v112
	v_max_f32_e32 v113, 0, v113
	v_max_f32_e32 v114, 0, v114
	v_max_f32_e32 v115, 0, v115
	v_max_f32_e32 v116, 0, v116
	v_max_f32_e32 v117, 0, v117
	v_max_f32_e32 v118, 0, v118
	v_max_f32_e32 v119, 0, v119
	v_pk_mul_f32 v[112:113], v[112:113], v[112:113]
	v_pk_mul_f32 v[114:115], v[114:115], v[114:115]
	v_pk_mul_f32 v[116:117], v[116:117], v[116:117]
	v_pk_mul_f32 v[118:119], v[118:119], v[118:119]
	v_cvt_pk_bf16_f32 v116, v116, v117
	v_cvt_pk_bf16_f32 v117, v118, v119
	v_cvt_pk_bf16_f32 v118, v112, v113
	v_cvt_pk_bf16_f32 v119, v114, v115
	global_store_dwordx4 v239, v[116:119], s[84:85] offset:256
	v_pk_mul_f32 v[104:105], v[104:105], v[182:183] op_sel:[0,1] op_sel_hi:[1,1]
	v_pk_mul_f32 v[106:107], v[106:107], v[182:183] op_sel:[0,1] op_sel_hi:[1,1]
	v_pk_mul_f32 v[108:109], v[108:109], v[182:183] op_sel:[0,1] op_sel_hi:[1,1]
	v_pk_mul_f32 v[110:111], v[110:111], v[182:183] op_sel:[0,1] op_sel_hi:[1,1]
	v_max_f32_e32 v104, 0, v104
	v_max_f32_e32 v105, 0, v105
	v_max_f32_e32 v106, 0, v106
	v_max_f32_e32 v107, 0, v107
	v_max_f32_e32 v108, 0, v108
	v_max_f32_e32 v109, 0, v109
	v_max_f32_e32 v110, 0, v110
	v_max_f32_e32 v111, 0, v111
	v_pk_mul_f32 v[104:105], v[104:105], v[104:105]
	v_pk_mul_f32 v[106:107], v[106:107], v[106:107]
	v_pk_mul_f32 v[108:109], v[108:109], v[108:109]
	v_pk_mul_f32 v[110:111], v[110:111], v[110:111]
	v_cvt_pk_bf16_f32 v108, v108, v109
	v_cvt_pk_bf16_f32 v109, v110, v111
	v_cvt_pk_bf16_f32 v110, v104, v105
	v_cvt_pk_bf16_f32 v111, v106, v107
	s_add_u32 s100, s84, 0x20000
	s_addc_u32 s101, s85, 0
	global_store_dwordx4 v239, v[108:111], s[100:101]
	v_pk_mul_f32 v[96:97], v[96:97], v[182:183] op_sel:[0,1] op_sel_hi:[1,1]
	v_pk_mul_f32 v[98:99], v[98:99], v[182:183] op_sel:[0,1] op_sel_hi:[1,1]
	v_pk_mul_f32 v[100:101], v[100:101], v[182:183] op_sel:[0,1] op_sel_hi:[1,1]
	v_pk_mul_f32 v[102:103], v[102:103], v[182:183] op_sel:[0,1] op_sel_hi:[1,1]
	v_max_f32_e32 v96, 0, v96
	v_max_f32_e32 v97, 0, v97
	v_max_f32_e32 v98, 0, v98
	v_max_f32_e32 v99, 0, v99
	v_max_f32_e32 v100, 0, v100
	v_max_f32_e32 v101, 0, v101
	v_max_f32_e32 v102, 0, v102
	v_max_f32_e32 v103, 0, v103
	v_pk_mul_f32 v[96:97], v[96:97], v[96:97]
	v_pk_mul_f32 v[98:99], v[98:99], v[98:99]
	v_pk_mul_f32 v[100:101], v[100:101], v[100:101]
	v_pk_mul_f32 v[102:103], v[102:103], v[102:103]
	v_cvt_pk_bf16_f32 v100, v100, v101
	v_cvt_pk_bf16_f32 v101, v102, v103
	v_cvt_pk_bf16_f32 v102, v96, v97
	v_cvt_pk_bf16_f32 v103, v98, v99
	s_add_u32 s100, s84, 0x20000
	s_addc_u32 s101, s85, 0
	global_store_dwordx4 v239, v[100:103], s[100:101] offset:256
	v_pk_mul_f32 v[88:89], v[88:89], v[184:185] op_sel_hi:[1,0]
	v_pk_mul_f32 v[90:91], v[90:91], v[184:185] op_sel_hi:[1,0]
	v_pk_mul_f32 v[92:93], v[92:93], v[184:185] op_sel_hi:[1,0]
	v_pk_mul_f32 v[94:95], v[94:95], v[184:185] op_sel_hi:[1,0]
	v_max_f32_e32 v88, 0, v88
	v_max_f32_e32 v89, 0, v89
	v_max_f32_e32 v90, 0, v90
	v_max_f32_e32 v91, 0, v91
	v_max_f32_e32 v92, 0, v92
	v_max_f32_e32 v93, 0, v93
	v_max_f32_e32 v94, 0, v94
	v_max_f32_e32 v95, 0, v95
	v_pk_mul_f32 v[88:89], v[88:89], v[88:89]
	v_pk_mul_f32 v[90:91], v[90:91], v[90:91]
	v_pk_mul_f32 v[92:93], v[92:93], v[92:93]
	v_pk_mul_f32 v[94:95], v[94:95], v[94:95]
	v_cvt_pk_bf16_f32 v92, v92, v93
	v_cvt_pk_bf16_f32 v93, v94, v95
	v_cvt_pk_bf16_f32 v94, v88, v89
	v_cvt_pk_bf16_f32 v95, v90, v91
	s_add_u32 s100, s84, 0x40000
	s_addc_u32 s101, s85, 0
	global_store_dwordx4 v239, v[92:95], s[100:101]
	v_pk_mul_f32 v[80:81], v[80:81], v[184:185] op_sel_hi:[1,0]
	v_pk_mul_f32 v[82:83], v[82:83], v[184:185] op_sel_hi:[1,0]
	v_pk_mul_f32 v[84:85], v[84:85], v[184:185] op_sel_hi:[1,0]
	v_pk_mul_f32 v[86:87], v[86:87], v[184:185] op_sel_hi:[1,0]
	v_max_f32_e32 v80, 0, v80
	v_max_f32_e32 v81, 0, v81
	v_max_f32_e32 v82, 0, v82
	v_max_f32_e32 v83, 0, v83
	v_max_f32_e32 v84, 0, v84
	v_max_f32_e32 v85, 0, v85
	v_max_f32_e32 v86, 0, v86
	v_max_f32_e32 v87, 0, v87
	v_pk_mul_f32 v[80:81], v[80:81], v[80:81]
	v_pk_mul_f32 v[82:83], v[82:83], v[82:83]
	v_pk_mul_f32 v[84:85], v[84:85], v[84:85]
	v_pk_mul_f32 v[86:87], v[86:87], v[86:87]
	v_cvt_pk_bf16_f32 v84, v84, v85
	v_cvt_pk_bf16_f32 v85, v86, v87
	v_cvt_pk_bf16_f32 v86, v80, v81
	v_cvt_pk_bf16_f32 v87, v82, v83
	s_add_u32 s100, s84, 0x40000
	s_addc_u32 s101, s85, 0
	global_store_dwordx4 v239, v[84:87], s[100:101] offset:256
	v_pk_mul_f32 v[72:73], v[72:73], v[184:185] op_sel:[0,1] op_sel_hi:[1,1]
	v_pk_mul_f32 v[74:75], v[74:75], v[184:185] op_sel:[0,1] op_sel_hi:[1,1]
	v_pk_mul_f32 v[76:77], v[76:77], v[184:185] op_sel:[0,1] op_sel_hi:[1,1]
	v_pk_mul_f32 v[78:79], v[78:79], v[184:185] op_sel:[0,1] op_sel_hi:[1,1]
	v_max_f32_e32 v72, 0, v72
	v_max_f32_e32 v73, 0, v73
	v_max_f32_e32 v74, 0, v74
	v_max_f32_e32 v75, 0, v75
	v_max_f32_e32 v76, 0, v76
	v_max_f32_e32 v77, 0, v77
	v_max_f32_e32 v78, 0, v78
	v_max_f32_e32 v79, 0, v79
	v_pk_mul_f32 v[72:73], v[72:73], v[72:73]
	v_pk_mul_f32 v[74:75], v[74:75], v[74:75]
	v_pk_mul_f32 v[76:77], v[76:77], v[76:77]
	v_pk_mul_f32 v[78:79], v[78:79], v[78:79]
	v_cvt_pk_bf16_f32 v76, v76, v77
	v_cvt_pk_bf16_f32 v77, v78, v79
	v_cvt_pk_bf16_f32 v78, v72, v73
	v_cvt_pk_bf16_f32 v79, v74, v75
	s_add_u32 s100, s84, 0x60000
	s_addc_u32 s101, s85, 0
	global_store_dwordx4 v239, v[76:79], s[100:101]
	v_pk_mul_f32 v[64:65], v[64:65], v[184:185] op_sel:[0,1] op_sel_hi:[1,1]
	v_pk_mul_f32 v[66:67], v[66:67], v[184:185] op_sel:[0,1] op_sel_hi:[1,1]
	v_pk_mul_f32 v[68:69], v[68:69], v[184:185] op_sel:[0,1] op_sel_hi:[1,1]
	v_pk_mul_f32 v[70:71], v[70:71], v[184:185] op_sel:[0,1] op_sel_hi:[1,1]
	v_max_f32_e32 v64, 0, v64
	v_max_f32_e32 v65, 0, v65
	v_max_f32_e32 v66, 0, v66
	v_max_f32_e32 v67, 0, v67
	v_max_f32_e32 v68, 0, v68
	v_max_f32_e32 v69, 0, v69
	v_max_f32_e32 v70, 0, v70
	v_max_f32_e32 v71, 0, v71
	v_pk_mul_f32 v[64:65], v[64:65], v[64:65]
	v_pk_mul_f32 v[66:67], v[66:67], v[66:67]
	v_pk_mul_f32 v[68:69], v[68:69], v[68:69]
	v_pk_mul_f32 v[70:71], v[70:71], v[70:71]
	v_cvt_pk_bf16_f32 v68, v68, v69
	v_cvt_pk_bf16_f32 v69, v70, v71
	v_cvt_pk_bf16_f32 v70, v64, v65
	v_cvt_pk_bf16_f32 v71, v66, v67
	s_add_u32 s100, s84, 0x60000
	s_addc_u32 s101, s85, 0
	global_store_dwordx4 v239, v[68:71], s[100:101] offset:256
	v_pk_mul_f32 v[56:57], v[56:57], v[186:187] op_sel_hi:[1,0]
	v_pk_mul_f32 v[58:59], v[58:59], v[186:187] op_sel_hi:[1,0]
	v_pk_mul_f32 v[60:61], v[60:61], v[186:187] op_sel_hi:[1,0]
	v_pk_mul_f32 v[62:63], v[62:63], v[186:187] op_sel_hi:[1,0]
	v_max_f32_e32 v56, 0, v56
	v_max_f32_e32 v57, 0, v57
	v_max_f32_e32 v58, 0, v58
	v_max_f32_e32 v59, 0, v59
	v_max_f32_e32 v60, 0, v60
	v_max_f32_e32 v61, 0, v61
	v_max_f32_e32 v62, 0, v62
	v_max_f32_e32 v63, 0, v63
	v_pk_mul_f32 v[56:57], v[56:57], v[56:57]
	v_pk_mul_f32 v[58:59], v[58:59], v[58:59]
	v_pk_mul_f32 v[60:61], v[60:61], v[60:61]
	v_pk_mul_f32 v[62:63], v[62:63], v[62:63]
	v_cvt_pk_bf16_f32 v60, v60, v61
	v_cvt_pk_bf16_f32 v61, v62, v63
	v_cvt_pk_bf16_f32 v62, v56, v57
	v_cvt_pk_bf16_f32 v63, v58, v59
	s_add_u32 s100, s84, 0x100000
	s_addc_u32 s101, s85, 0
	global_store_dwordx4 v239, v[60:63], s[100:101]
	v_pk_mul_f32 v[48:49], v[48:49], v[186:187] op_sel_hi:[1,0]
	v_pk_mul_f32 v[50:51], v[50:51], v[186:187] op_sel_hi:[1,0]
	v_pk_mul_f32 v[52:53], v[52:53], v[186:187] op_sel_hi:[1,0]
	v_pk_mul_f32 v[54:55], v[54:55], v[186:187] op_sel_hi:[1,0]
	v_max_f32_e32 v48, 0, v48
	v_max_f32_e32 v49, 0, v49
	v_max_f32_e32 v50, 0, v50
	v_max_f32_e32 v51, 0, v51
	v_max_f32_e32 v52, 0, v52
	v_max_f32_e32 v53, 0, v53
	v_max_f32_e32 v54, 0, v54
	v_max_f32_e32 v55, 0, v55
	v_pk_mul_f32 v[48:49], v[48:49], v[48:49]
	v_pk_mul_f32 v[50:51], v[50:51], v[50:51]
	v_pk_mul_f32 v[52:53], v[52:53], v[52:53]
	v_pk_mul_f32 v[54:55], v[54:55], v[54:55]
	v_cvt_pk_bf16_f32 v52, v52, v53
	v_cvt_pk_bf16_f32 v53, v54, v55
	v_cvt_pk_bf16_f32 v54, v48, v49
	v_cvt_pk_bf16_f32 v55, v50, v51
	s_add_u32 s100, s84, 0x100000
	s_addc_u32 s101, s85, 0
	global_store_dwordx4 v239, v[52:55], s[100:101] offset:256
	v_pk_mul_f32 v[40:41], v[40:41], v[186:187] op_sel:[0,1] op_sel_hi:[1,1]
	v_pk_mul_f32 v[42:43], v[42:43], v[186:187] op_sel:[0,1] op_sel_hi:[1,1]
	v_pk_mul_f32 v[44:45], v[44:45], v[186:187] op_sel:[0,1] op_sel_hi:[1,1]
	v_pk_mul_f32 v[46:47], v[46:47], v[186:187] op_sel:[0,1] op_sel_hi:[1,1]
	v_max_f32_e32 v40, 0, v40
	v_max_f32_e32 v41, 0, v41
	v_max_f32_e32 v42, 0, v42
	v_max_f32_e32 v43, 0, v43
	v_max_f32_e32 v44, 0, v44
	v_max_f32_e32 v45, 0, v45
	v_max_f32_e32 v46, 0, v46
	v_max_f32_e32 v47, 0, v47
	v_pk_mul_f32 v[40:41], v[40:41], v[40:41]
	v_pk_mul_f32 v[42:43], v[42:43], v[42:43]
	v_pk_mul_f32 v[44:45], v[44:45], v[44:45]
	v_pk_mul_f32 v[46:47], v[46:47], v[46:47]
	v_cvt_pk_bf16_f32 v230, v44, v45
	v_cvt_pk_bf16_f32 v231, v46, v47
	v_cvt_pk_bf16_f32 v232, v40, v41
	v_cvt_pk_bf16_f32 v233, v42, v43
	v_pk_mul_f32 v[32:33], v[32:33], v[186:187] op_sel:[0,1] op_sel_hi:[1,1]
	v_pk_mul_f32 v[34:35], v[34:35], v[186:187] op_sel:[0,1] op_sel_hi:[1,1]
	v_pk_mul_f32 v[36:37], v[36:37], v[186:187] op_sel:[0,1] op_sel_hi:[1,1]
	v_pk_mul_f32 v[38:39], v[38:39], v[186:187] op_sel:[0,1] op_sel_hi:[1,1]
	v_max_f32_e32 v32, 0, v32
	v_max_f32_e32 v33, 0, v33
	v_max_f32_e32 v34, 0, v34
	v_max_f32_e32 v35, 0, v35
	v_max_f32_e32 v36, 0, v36
	v_max_f32_e32 v37, 0, v37
	v_max_f32_e32 v38, 0, v38
	v_max_f32_e32 v39, 0, v39
	v_pk_mul_f32 v[32:33], v[32:33], v[32:33]
	v_pk_mul_f32 v[34:35], v[34:35], v[34:35]
	v_pk_mul_f32 v[36:37], v[36:37], v[36:37]
	v_pk_mul_f32 v[38:39], v[38:39], v[38:39]
	v_cvt_pk_bf16_f32 v234, v36, v37
	v_cvt_pk_bf16_f32 v235, v38, v39
	v_cvt_pk_bf16_f32 v236, v32, v33
	v_cvt_pk_bf16_f32 v237, v34, v35
	v_pk_mul_f32 v[24:25], v[24:25], v[188:189] op_sel_hi:[1,0]
	v_pk_mul_f32 v[26:27], v[26:27], v[188:189] op_sel_hi:[1,0]
	v_pk_mul_f32 v[28:29], v[28:29], v[188:189] op_sel_hi:[1,0]
	v_pk_mul_f32 v[30:31], v[30:31], v[188:189] op_sel_hi:[1,0]
	v_max_f32_e32 v24, 0, v24
	v_max_f32_e32 v25, 0, v25
	v_max_f32_e32 v26, 0, v26
	v_max_f32_e32 v27, 0, v27
	v_max_f32_e32 v28, 0, v28
	v_max_f32_e32 v29, 0, v29
	v_max_f32_e32 v30, 0, v30
	v_max_f32_e32 v31, 0, v31
	v_pk_mul_f32 v[24:25], v[24:25], v[24:25]
	v_pk_mul_f32 v[26:27], v[26:27], v[26:27]
	v_pk_mul_f32 v[28:29], v[28:29], v[28:29]
	v_pk_mul_f32 v[30:31], v[30:31], v[30:31]
	v_cvt_pk_bf16_f32 v240, v28, v29
	v_cvt_pk_bf16_f32 v241, v30, v31
	v_cvt_pk_bf16_f32 v242, v24, v25
	v_cvt_pk_bf16_f32 v243, v26, v27
	v_pk_mul_f32 v[16:17], v[16:17], v[188:189] op_sel_hi:[1,0]
	v_pk_mul_f32 v[18:19], v[18:19], v[188:189] op_sel_hi:[1,0]
	v_pk_mul_f32 v[20:21], v[20:21], v[188:189] op_sel_hi:[1,0]
	v_pk_mul_f32 v[22:23], v[22:23], v[188:189] op_sel_hi:[1,0]
	v_max_f32_e32 v16, 0, v16
	v_max_f32_e32 v17, 0, v17
	v_max_f32_e32 v18, 0, v18
	v_max_f32_e32 v19, 0, v19
	v_max_f32_e32 v20, 0, v20
	v_max_f32_e32 v21, 0, v21
	v_max_f32_e32 v22, 0, v22
	v_max_f32_e32 v23, 0, v23
	v_pk_mul_f32 v[16:17], v[16:17], v[16:17]
	v_pk_mul_f32 v[18:19], v[18:19], v[18:19]
	v_pk_mul_f32 v[20:21], v[20:21], v[20:21]
	v_pk_mul_f32 v[22:23], v[22:23], v[22:23]
	v_cvt_pk_bf16_f32 v244, v20, v21
	v_cvt_pk_bf16_f32 v245, v22, v23
	v_cvt_pk_bf16_f32 v246, v16, v17
	v_cvt_pk_bf16_f32 v247, v18, v19
	v_pk_mul_f32 v[8:9], v[8:9], v[188:189] op_sel:[0,1] op_sel_hi:[1,1]
	v_pk_mul_f32 v[10:11], v[10:11], v[188:189] op_sel:[0,1] op_sel_hi:[1,1]
	v_pk_mul_f32 v[12:13], v[12:13], v[188:189] op_sel:[0,1] op_sel_hi:[1,1]
	v_pk_mul_f32 v[14:15], v[14:15], v[188:189] op_sel:[0,1] op_sel_hi:[1,1]
	v_max_f32_e32 v8, 0, v8
	v_max_f32_e32 v9, 0, v9
	v_max_f32_e32 v10, 0, v10
	v_max_f32_e32 v11, 0, v11
	v_max_f32_e32 v12, 0, v12
	v_max_f32_e32 v13, 0, v13
	v_max_f32_e32 v14, 0, v14
	v_max_f32_e32 v15, 0, v15
	v_pk_mul_f32 v[8:9], v[8:9], v[8:9]
	v_pk_mul_f32 v[10:11], v[10:11], v[10:11]
	v_pk_mul_f32 v[12:13], v[12:13], v[12:13]
	v_pk_mul_f32 v[14:15], v[14:15], v[14:15]
	v_cvt_pk_bf16_f32 v248, v12, v13
	v_cvt_pk_bf16_f32 v249, v14, v15
	v_cvt_pk_bf16_f32 v250, v8, v9
	v_cvt_pk_bf16_f32 v251, v10, v11
	v_pk_mul_f32 v[0:1], v[0:1], v[188:189] op_sel:[0,1] op_sel_hi:[1,1]
	v_pk_mul_f32 v[2:3], v[2:3], v[188:189] op_sel:[0,1] op_sel_hi:[1,1]
	v_pk_mul_f32 v[4:5], v[4:5], v[188:189] op_sel:[0,1] op_sel_hi:[1,1]
	v_pk_mul_f32 v[6:7], v[6:7], v[188:189] op_sel:[0,1] op_sel_hi:[1,1]
	v_max_f32_e32 v0, 0, v0
	v_max_f32_e32 v1, 0, v1
	v_max_f32_e32 v2, 0, v2
	v_max_f32_e32 v3, 0, v3
	v_max_f32_e32 v4, 0, v4
	v_max_f32_e32 v5, 0, v5
	v_max_f32_e32 v6, 0, v6
	v_max_f32_e32 v7, 0, v7
	v_pk_mul_f32 v[0:1], v[0:1], v[0:1]
	v_pk_mul_f32 v[2:3], v[2:3], v[2:3]
	v_pk_mul_f32 v[4:5], v[4:5], v[4:5]
	v_pk_mul_f32 v[6:7], v[6:7], v[6:7]
	v_cvt_pk_bf16_f32 v252, v4, v5
	v_cvt_pk_bf16_f32 v253, v6, v7
	v_cvt_pk_bf16_f32 v254, v0, v1
	v_cvt_pk_bf16_f32 v255, v2, v3
	s_mov_b64 s[56:57], s[54:55]
	s_and_b64 vcc, exec, s[8:9]
	s_mov_b32 s67, s38
	s_mov_b32 s10, s50
	s_mov_b64 s[12:13], s[52:53]
	s_mov_b64 s[98:99], s[84:85]
	s_mov_b32 s32, 1
	s_cbranch_vccz .LBB0_980
	s_add_u32 s100, s84, 0x120000
	s_addc_u32 s101, s85, 0
	global_store_dwordx4 v239, v[230:233], s[100:101]
	s_add_u32 s100, s84, 0x120000
	s_addc_u32 s101, s85, 0
	global_store_dwordx4 v239, v[234:237], s[100:101] offset:256
	s_add_u32 s100, s84, 0x140000
	s_addc_u32 s101, s85, 0
	global_store_dwordx4 v239, v[240:243], s[100:101]
	s_add_u32 s100, s84, 0x140000
	s_addc_u32 s101, s85, 0
	global_store_dwordx4 v239, v[244:247], s[100:101] offset:256
	s_add_u32 s100, s84, 0x160000
	s_addc_u32 s101, s85, 0
	global_store_dwordx4 v239, v[248:251], s[100:101]
	s_add_u32 s100, s84, 0x160000
	s_addc_u32 s101, s85, 0
	global_store_dwordx4 v239, v[252:255], s[100:101] offset:256
	s_waitcnt vmcnt(0)
	s_cmpk_gt_u32 s0, 0xff
	s_cbranch_scc1 .LBB0_991
	s_barrier

	.amdhsa_kernel _Z6k_mega6Params
		.amdhsa_group_segment_fixed_size 0
		.amdhsa_private_segment_fixed_size 0
		.amdhsa_kernarg_size 448
		.amdhsa_user_sgpr_count 2
		.amdhsa_user_sgpr_dispatch_ptr 0
		.amdhsa_user_sgpr_queue_ptr 0
		.amdhsa_user_sgpr_kernarg_segment_ptr 1
		.amdhsa_user_sgpr_dispatch_id 0
		.amdhsa_user_sgpr_kernarg_preload_length 0
		.amdhsa_user_sgpr_kernarg_preload_offset 0
		.amdhsa_user_sgpr_private_segment_size 0
		.amdhsa_uses_dynamic_stack 0
		.amdhsa_enable_private_segment 0
		.amdhsa_system_sgpr_workgroup_id_x 1
		.amdhsa_system_sgpr_workgroup_id_y 0
		.amdhsa_system_sgpr_workgroup_id_z 0
		.amdhsa_system_sgpr_workgroup_info 0
		.amdhsa_system_vgpr_workitem_id 2
		.amdhsa_next_free_vgpr 256
		.amdhsa_next_free_sgpr 102
		.amdhsa_accum_offset 256
		.amdhsa_reserve_vcc 1
		.amdhsa_float_round_mode_32 0
		.amdhsa_float_round_mode_16_64 0
		.amdhsa_float_denorm_mode_32 3
		.amdhsa_float_denorm_mode_16_64 3
		.amdhsa_dx10_clamp 1
		.amdhsa_ieee_mode 1
		.amdhsa_fp16_overflow 0
		.amdhsa_tg_split 0
		.amdhsa_exception_fp_ieee_invalid_op 0
		.amdhsa_exception_fp_denorm_src 0
		.amdhsa_exception_fp_ieee_div_zero 0
		.amdhsa_exception_fp_ieee_overflow 0
		.amdhsa_exception_fp_ieee_underflow 0
		.amdhsa_exception_fp_ieee_inexact 0
		.amdhsa_exception_int_div_zero 0
	.end_amdhsa_kernel

amdhsa.kernels:
  - .agpr_count:     0
    .args:
      - .offset:         0
        .size:           192
        .value_kind:     by_value
      - .offset:         192
        .size:           4
        .value_kind:     hidden_block_count_x
      - .offset:         196
        .size:           4
        .value_kind:     hidden_block_count_y
      - .offset:         200
        .size:           4
        .value_kind:     hidden_block_count_z
      - .offset:         204
        .size:           2
        .value_kind:     hidden_group_size_x
      - .offset:         206
        .size:           2
        .value_kind:     hidden_group_size_y
      - .offset:         208
        .size:           2
        .value_kind:     hidden_group_size_z
      - .offset:         210
        .size:           2
        .value_kind:     hidden_remainder_x
      - .offset:         212
        .size:           2
        .value_kind:     hidden_remainder_y
      - .offset:         214
        .size:           2
        .value_kind:     hidden_remainder_z
      - .offset:         232
        .size:           8
        .value_kind:     hidden_global_offset_x
      - .offset:         240
        .size:           8
        .value_kind:     hidden_global_offset_y
      - .offset:         248
        .size:           8
        .value_kind:     hidden_global_offset_z
      - .offset:         256
        .size:           2
        .value_kind:     hidden_grid_dims
      - .offset:         280
        .size:           8
        .value_kind:     hidden_multigrid_sync_arg
      - .offset:         312
        .size:           4
        .value_kind:     hidden_dynamic_lds_size
    .group_segment_fixed_size: 0
    .kernarg_segment_align: 8
    .kernarg_segment_size: 448
    .language:       OpenCL C
    .language_version:
      - 2
      - 0
    .max_flat_workgroup_size: 512
    .name:           _Z6k_mega6Params
    .private_segment_fixed_size: 0
    .sgpr_count:     108
    .sgpr_spill_count: 26
    .symbol:         _Z6k_mega6Params.kd
    .uniform_work_group_size: 1
    .uses_dynamic_stack: false
    .vgpr_count:     256
    .vgpr_spill_count: 0
    .wavefront_size: 64
